# best + K-loop LDS-DMAs use saddr+voffset form (20 64-bit VALU address adds removed in P1/P4/P5/P6 loops)
# baseline (speedup 1.0000x reference)
.LBB0_124:
	ds_read_b128 v[160:163], v202
	ds_read_b128 v[164:167], v202 offset:1024
	ds_read_b128 v[168:171], v202 offset:2048
	ds_read_b128 v[172:175], v202 offset:3072
	ds_read_b128 v[208:211], v203
	ds_read_b128 v[212:215], v203 offset:1024
	ds_read_b128 v[218:221], v203 offset:2048
	ds_read_b128 v[222:225], v203 offset:3072
	s_add_i32 s15, s14, 2
	s_add_u32 s10, s12, s6
	s_addc_u32 s11, s13, s7
	s_cmpk_eq_i32 s6, 0x700
	s_cselect_b32 s16, s85, s9
	s_cselect_b32 s17, s84, s8
	s_cselect_b32 s86, 0, s15
	s_cselect_b32 s11, s57, s11
	s_cselect_b32 s10, s56, s10
	v_lshl_add_u64 v[192:193], v[156:157], 0, s[6:7]
	s_add_i32 m0, s39, 0xc000
	ds_read_b128 v[226:229], v204
	ds_read_b128 v[230:233], v204 offset:1024
	ds_read_b128 v[234:237], v204 offset:2048
	ds_read_b128 v[238:241], v204 offset:3072
	ds_read_b128 v[242:245], v204 offset:4096
	ds_read_b128 v[246:249], v204 offset:5120
	ds_read_b128 v[250:253], v204 offset:6144
	ds_read_b128 v[186:189], v204 offset:7168
	global_load_lds_dwordx4 v[192:193], off
	v_lshl_add_u64 v[192:193], v[158:159], 0, s[6:7]
	s_add_i32 m0, s39, 0xe000
	s_nop 0
	global_load_lds_dwordx4 v[192:193], off
	s_waitcnt vmcnt(8)
	s_waitcnt lgkmcnt(0)
	s_barrier
	s_setprio 1
	v_mfma_f32_16x16x32_bf16 v[124:127], v[160:163], v[226:229], v[124:127]
	v_mfma_f32_16x16x32_bf16 v[120:123], v[168:171], v[226:229], v[120:123]
	v_mfma_f32_16x16x32_bf16 v[108:111], v[160:163], v[234:237], v[108:111]
	v_mfma_f32_16x16x32_bf16 v[104:107], v[168:171], v[234:237], v[104:107]
	v_mfma_f32_16x16x32_bf16 v[92:95], v[160:163], v[242:245], v[92:95]
	v_mfma_f32_16x16x32_bf16 v[88:91], v[168:171], v[242:245], v[88:91]
	v_mfma_f32_16x16x32_bf16 v[76:79], v[160:163], v[250:253], v[76:79]
	v_mfma_f32_16x16x32_bf16 v[72:75], v[168:171], v[250:253], v[72:75]
	v_mfma_f32_16x16x32_bf16 v[124:127], v[164:167], v[230:233], v[124:127]
	v_mfma_f32_16x16x32_bf16 v[120:123], v[172:175], v[230:233], v[120:123]
	v_mfma_f32_16x16x32_bf16 v[108:111], v[164:167], v[238:241], v[108:111]
	v_mfma_f32_16x16x32_bf16 v[104:107], v[172:175], v[238:241], v[104:107]
	v_mfma_f32_16x16x32_bf16 v[92:95], v[164:167], v[246:249], v[92:95]
	v_mfma_f32_16x16x32_bf16 v[88:91], v[172:175], v[246:249], v[88:91]
	v_mfma_f32_16x16x32_bf16 v[76:79], v[164:167], v[186:189], v[76:79]
	v_mfma_f32_16x16x32_bf16 v[72:75], v[172:175], v[186:189], v[72:75]
	s_setprio 0
	s_setprio 1
	v_mfma_f32_16x16x32_bf16 v[116:119], v[208:211], v[226:229], v[116:119]
	v_mfma_f32_16x16x32_bf16 v[112:115], v[218:221], v[226:229], v[112:115]
	v_mfma_f32_16x16x32_bf16 v[100:103], v[208:211], v[234:237], v[100:103]
	v_mfma_f32_16x16x32_bf16 v[96:99], v[218:221], v[234:237], v[96:99]
	v_mfma_f32_16x16x32_bf16 v[84:87], v[208:211], v[242:245], v[84:87]
	v_mfma_f32_16x16x32_bf16 v[80:83], v[218:221], v[242:245], v[80:83]
	v_mfma_f32_16x16x32_bf16 v[68:71], v[208:211], v[250:253], v[68:71]
	v_mfma_f32_16x16x32_bf16 v[64:67], v[218:221], v[250:253], v[64:67]
	v_mfma_f32_16x16x32_bf16 v[116:119], v[212:215], v[230:233], v[116:119]
	v_mfma_f32_16x16x32_bf16 v[112:115], v[222:225], v[230:233], v[112:115]
	v_mfma_f32_16x16x32_bf16 v[100:103], v[212:215], v[238:241], v[100:103]
	v_mfma_f32_16x16x32_bf16 v[96:99], v[222:225], v[238:241], v[96:99]
	v_mfma_f32_16x16x32_bf16 v[84:87], v[212:215], v[246:249], v[84:87]
	v_mfma_f32_16x16x32_bf16 v[80:83], v[222:225], v[246:249], v[80:83]
	v_mfma_f32_16x16x32_bf16 v[68:71], v[212:215], v[186:189], v[68:71]
	v_mfma_f32_16x16x32_bf16 v[64:67], v[222:225], v[186:189], v[64:67]
	s_setprio 0
	s_barrier
	s_add_i32 s18, s94, s97
	v_lshl_add_u64 v[192:193], s[10:11], 0, v[132:133]
	s_mov_b32 m0, s18
	ds_read_b128 v[186:189], v204 offset:16384
	ds_read_b128 v[226:229], v204 offset:17408
	ds_read_b128 v[230:233], v204 offset:18432
	ds_read_b128 v[234:237], v204 offset:19456
	ds_read_b128 v[238:241], v204 offset:20480
	ds_read_b128 v[242:245], v204 offset:21504
	ds_read_b128 v[246:249], v204 offset:22528
	ds_read_b128 v[250:253], v204 offset:23552
	global_load_lds_dwordx4 v[192:193], off
	s_add_i32 m0, s18, 0x2000
	s_add_u32 s18, s10, 0x40000
	v_lshl_add_u64 v[196:197], s[10:11], 0, v[136:137]
	s_addc_u32 s19, s11, 0
	s_add_i32 s20, s95, s97
	global_load_lds_dwordx4 v[196:197], off
	s_mov_b32 m0, s20
	s_nop 0
	global_load_lds_dwordx4 v132, s[18:19]
	v_lshl_add_u64 v[176:177], s[18:19], 0, v[136:137]
	s_add_i32 m0, s20, 0x2000
	s_lshl_b64 s[18:19], s[86:87], 7
	s_add_u32 s18, s17, s18
	s_addc_u32 s19, s16, s19
	global_load_lds_dwordx4 v[176:177], off
	s_mov_b32 m0, s39
	s_nop 0
	global_load_lds_dwordx4 v130, s[18:19]
	s_mov_b32 m0, s91
	s_nop 0
	global_load_lds_dwordx4 v134, s[18:19]
	s_waitcnt vmcnt(8)
	s_waitcnt lgkmcnt(0)
	s_barrier
	s_setprio 1
	v_mfma_f32_16x16x32_bf16 v[60:63], v[160:163], v[186:189], v[60:63]
	v_mfma_f32_16x16x32_bf16 v[56:59], v[168:171], v[186:189], v[56:59]
	v_mfma_f32_16x16x32_bf16 v[44:47], v[160:163], v[230:233], v[44:47]
	v_mfma_f32_16x16x32_bf16 v[40:43], v[168:171], v[230:233], v[40:43]
	v_mfma_f32_16x16x32_bf16 v[28:31], v[160:163], v[238:241], v[28:31]
	v_mfma_f32_16x16x32_bf16 v[24:27], v[168:171], v[238:241], v[24:27]
	v_mfma_f32_16x16x32_bf16 v[12:15], v[160:163], v[246:249], v[12:15]
	v_mfma_f32_16x16x32_bf16 v[8:11], v[168:171], v[246:249], v[8:11]
	v_mfma_f32_16x16x32_bf16 v[60:63], v[164:167], v[226:229], v[60:63]
	v_mfma_f32_16x16x32_bf16 v[56:59], v[172:175], v[226:229], v[56:59]
	v_mfma_f32_16x16x32_bf16 v[44:47], v[164:167], v[234:237], v[44:47]
	v_mfma_f32_16x16x32_bf16 v[40:43], v[172:175], v[234:237], v[40:43]
	v_mfma_f32_16x16x32_bf16 v[28:31], v[164:167], v[242:245], v[28:31]
	v_mfma_f32_16x16x32_bf16 v[24:27], v[172:175], v[242:245], v[24:27]
	v_mfma_f32_16x16x32_bf16 v[12:15], v[164:167], v[250:253], v[12:15]
	v_mfma_f32_16x16x32_bf16 v[8:11], v[172:175], v[250:253], v[8:11]
	s_setprio 0
	s_setprio 1
	v_mfma_f32_16x16x32_bf16 v[52:55], v[208:211], v[186:189], v[52:55]
	v_mfma_f32_16x16x32_bf16 v[48:51], v[218:221], v[186:189], v[48:51]
	v_mfma_f32_16x16x32_bf16 v[36:39], v[208:211], v[230:233], v[36:39]
	v_mfma_f32_16x16x32_bf16 v[32:35], v[218:221], v[230:233], v[32:35]
	v_mfma_f32_16x16x32_bf16 v[20:23], v[208:211], v[238:241], v[20:23]
	v_mfma_f32_16x16x32_bf16 v[16:19], v[218:221], v[238:241], v[16:19]
	v_mfma_f32_16x16x32_bf16 v[4:7], v[208:211], v[246:249], v[4:7]
	v_mfma_f32_16x16x32_bf16 v[0:3], v[218:221], v[246:249], v[0:3]
	v_mfma_f32_16x16x32_bf16 v[52:55], v[212:215], v[226:229], v[52:55]
	v_mfma_f32_16x16x32_bf16 v[48:51], v[222:225], v[226:229], v[48:51]
	v_mfma_f32_16x16x32_bf16 v[36:39], v[212:215], v[234:237], v[36:39]
	v_mfma_f32_16x16x32_bf16 v[32:35], v[222:225], v[234:237], v[32:35]
	v_mfma_f32_16x16x32_bf16 v[20:23], v[212:215], v[242:245], v[20:23]
	v_mfma_f32_16x16x32_bf16 v[16:19], v[222:225], v[242:245], v[16:19]
	v_mfma_f32_16x16x32_bf16 v[4:7], v[212:215], v[250:253], v[4:7]
	v_mfma_f32_16x16x32_bf16 v[0:3], v[222:225], v[250:253], v[0:3]
	s_setprio 0
	s_barrier
	s_add_i32 s20, 0, 0x18000
	v_add_u32_e32 v138, s20, v179
	s_add_i32 s21, 0, 0x1c000
	ds_read_b128 v[160:163], v138
	ds_read_b128 v[164:167], v138 offset:1024
	ds_read_b128 v[168:171], v138 offset:2048
	ds_read_b128 v[172:175], v138 offset:3072
	v_add_u32_e32 v138, s21, v179
	ds_read_b128 v[186:189], v138
	ds_read_b128 v[208:211], v138 offset:1024
	ds_read_b128 v[212:215], v138 offset:2048
	ds_read_b128 v[218:221], v138 offset:3072
	s_add_u32 s18, s18, 0x40000
	s_addc_u32 s19, s19, 0
	s_mov_b32 m0, s33
	ds_read_b128 v[222:225], v204 offset:32768
	ds_read_b128 v[226:229], v204 offset:33792
	ds_read_b128 v[230:233], v204 offset:34816
	ds_read_b128 v[234:237], v204 offset:35840
	ds_read_b128 v[238:241], v204 offset:36864
	ds_read_b128 v[242:245], v204 offset:37888
	ds_read_b128 v[246:249], v204 offset:38912
	ds_read_b128 v[250:253], v204 offset:39936
	global_load_lds_dwordx4 v130, s[18:19]
	s_mov_b32 m0, s58
	s_nop 0
	global_load_lds_dwordx4 v134, s[18:19]
	s_waitcnt vmcnt(8)
	s_waitcnt lgkmcnt(0)
	s_barrier
	s_setprio 1
	v_mfma_f32_16x16x32_bf16 v[124:127], v[160:163], v[222:225], v[124:127]
	v_mfma_f32_16x16x32_bf16 v[120:123], v[168:171], v[222:225], v[120:123]
	v_mfma_f32_16x16x32_bf16 v[108:111], v[160:163], v[230:233], v[108:111]
	v_mfma_f32_16x16x32_bf16 v[104:107], v[168:171], v[230:233], v[104:107]
	v_mfma_f32_16x16x32_bf16 v[92:95], v[160:163], v[238:241], v[92:95]
	v_mfma_f32_16x16x32_bf16 v[88:91], v[168:171], v[238:241], v[88:91]
	v_mfma_f32_16x16x32_bf16 v[76:79], v[160:163], v[246:249], v[76:79]
	v_mfma_f32_16x16x32_bf16 v[72:75], v[168:171], v[246:249], v[72:75]
	v_mfma_f32_16x16x32_bf16 v[124:127], v[164:167], v[226:229], v[124:127]
	v_mfma_f32_16x16x32_bf16 v[120:123], v[172:175], v[226:229], v[120:123]
	v_mfma_f32_16x16x32_bf16 v[108:111], v[164:167], v[234:237], v[108:111]
	v_mfma_f32_16x16x32_bf16 v[104:107], v[172:175], v[234:237], v[104:107]
	v_mfma_f32_16x16x32_bf16 v[92:95], v[164:167], v[242:245], v[92:95]
	v_mfma_f32_16x16x32_bf16 v[88:91], v[172:175], v[242:245], v[88:91]
	v_mfma_f32_16x16x32_bf16 v[76:79], v[164:167], v[250:253], v[76:79]
	v_mfma_f32_16x16x32_bf16 v[72:75], v[172:175], v[250:253], v[72:75]
	s_setprio 0
	s_setprio 1
	v_mfma_f32_16x16x32_bf16 v[116:119], v[186:189], v[222:225], v[116:119]
	v_mfma_f32_16x16x32_bf16 v[112:115], v[212:215], v[222:225], v[112:115]
	v_mfma_f32_16x16x32_bf16 v[100:103], v[186:189], v[230:233], v[100:103]
	v_mfma_f32_16x16x32_bf16 v[96:99], v[212:215], v[230:233], v[96:99]
	v_mfma_f32_16x16x32_bf16 v[84:87], v[186:189], v[238:241], v[84:87]
	v_mfma_f32_16x16x32_bf16 v[80:83], v[212:215], v[238:241], v[80:83]
	v_mfma_f32_16x16x32_bf16 v[68:71], v[186:189], v[246:249], v[68:71]
	v_mfma_f32_16x16x32_bf16 v[64:67], v[212:215], v[246:249], v[64:67]
	v_mfma_f32_16x16x32_bf16 v[116:119], v[208:211], v[226:229], v[116:119]
	v_mfma_f32_16x16x32_bf16 v[112:115], v[218:221], v[226:229], v[112:115]
	v_mfma_f32_16x16x32_bf16 v[100:103], v[208:211], v[234:237], v[100:103]
	v_mfma_f32_16x16x32_bf16 v[96:99], v[218:221], v[234:237], v[96:99]
	v_mfma_f32_16x16x32_bf16 v[84:87], v[208:211], v[242:245], v[84:87]
	v_mfma_f32_16x16x32_bf16 v[80:83], v[218:221], v[242:245], v[80:83]
	v_mfma_f32_16x16x32_bf16 v[68:71], v[208:211], v[250:253], v[68:71]
	v_mfma_f32_16x16x32_bf16 v[64:67], v[218:221], v[250:253], v[64:67]
	s_setprio 0
	s_barrier
	s_add_i32 s18, s20, s97
	v_lshl_add_u64 v[176:177], v[192:193], 0, s[64:65]
	s_mov_b32 m0, s18
	ds_read_b128 v[222:225], v204 offset:49152
	ds_read_b128 v[226:229], v204 offset:50176
	ds_read_b128 v[230:233], v204 offset:51200
	ds_read_b128 v[234:237], v204 offset:52224
	ds_read_b128 v[238:241], v204 offset:53248
	ds_read_b128 v[242:245], v204 offset:54272
	ds_read_b128 v[246:249], v204 offset:55296
	ds_read_b128 v[250:253], v204 offset:56320
	global_load_lds_dwordx4 v[176:177], off
	s_add_i32 m0, s18, 0x2000
	s_add_u32 s10, s10, 0x40080
	v_lshl_add_u64 v[176:177], v[196:197], 0, s[64:65]
	s_addc_u32 s11, s11, 0
	s_add_i32 s18, s21, s97
	global_load_lds_dwordx4 v[176:177], off
	s_mov_b32 m0, s18
	s_or_b32 s86, s86, 1
	global_load_lds_dwordx4 v132, s[10:11]
	v_lshl_add_u64 v[176:177], s[10:11], 0, v[136:137]
	s_add_i32 m0, s18, 0x2000
	s_lshl_b64 s[10:11], s[86:87], 7
	s_add_u32 s10, s17, s10
	s_addc_u32 s11, s16, s11
	global_load_lds_dwordx4 v[176:177], off
	s_mov_b32 m0, s92
	s_nop 0
	global_load_lds_dwordx4 v130, s[10:11]
	s_mov_b32 m0, s93
	s_nop 0
	global_load_lds_dwordx4 v134, s[10:11]
	s_waitcnt vmcnt(8)
	s_waitcnt lgkmcnt(0)
	s_barrier
	s_setprio 1
	v_mfma_f32_16x16x32_bf16 v[60:63], v[160:163], v[222:225], v[60:63]
	v_mfma_f32_16x16x32_bf16 v[56:59], v[168:171], v[222:225], v[56:59]
	v_mfma_f32_16x16x32_bf16 v[44:47], v[160:163], v[230:233], v[44:47]
	v_mfma_f32_16x16x32_bf16 v[40:43], v[168:171], v[230:233], v[40:43]
	v_mfma_f32_16x16x32_bf16 v[28:31], v[160:163], v[238:241], v[28:31]
	v_mfma_f32_16x16x32_bf16 v[24:27], v[168:171], v[238:241], v[24:27]
	v_mfma_f32_16x16x32_bf16 v[12:15], v[160:163], v[246:249], v[12:15]
	v_mfma_f32_16x16x32_bf16 v[8:11], v[168:171], v[246:249], v[8:11]
	v_mfma_f32_16x16x32_bf16 v[60:63], v[164:167], v[226:229], v[60:63]
	v_mfma_f32_16x16x32_bf16 v[56:59], v[172:175], v[226:229], v[56:59]
	v_mfma_f32_16x16x32_bf16 v[44:47], v[164:167], v[234:237], v[44:47]
	v_mfma_f32_16x16x32_bf16 v[40:43], v[172:175], v[234:237], v[40:43]
	v_mfma_f32_16x16x32_bf16 v[28:31], v[164:167], v[242:245], v[28:31]
	v_mfma_f32_16x16x32_bf16 v[24:27], v[172:175], v[242:245], v[24:27]
	v_mfma_f32_16x16x32_bf16 v[12:15], v[164:167], v[250:253], v[12:15]
	v_mfma_f32_16x16x32_bf16 v[8:11], v[172:175], v[250:253], v[8:11]
	s_setprio 0
	s_setprio 1
	v_mfma_f32_16x16x32_bf16 v[52:55], v[186:189], v[222:225], v[52:55]
	v_mfma_f32_16x16x32_bf16 v[48:51], v[212:215], v[222:225], v[48:51]
	v_mfma_f32_16x16x32_bf16 v[36:39], v[186:189], v[230:233], v[36:39]
	v_mfma_f32_16x16x32_bf16 v[32:35], v[212:215], v[230:233], v[32:35]
	v_mfma_f32_16x16x32_bf16 v[20:23], v[186:189], v[238:241], v[20:23]
	v_mfma_f32_16x16x32_bf16 v[16:19], v[212:215], v[238:241], v[16:19]
	v_mfma_f32_16x16x32_bf16 v[4:7], v[186:189], v[246:249], v[4:7]
	v_mfma_f32_16x16x32_bf16 v[0:3], v[212:215], v[246:249], v[0:3]
	v_mfma_f32_16x16x32_bf16 v[52:55], v[208:211], v[226:229], v[52:55]
	v_mfma_f32_16x16x32_bf16 v[48:51], v[218:221], v[226:229], v[48:51]
	v_mfma_f32_16x16x32_bf16 v[36:39], v[208:211], v[234:237], v[36:39]
	v_mfma_f32_16x16x32_bf16 v[32:35], v[218:221], v[234:237], v[32:35]
	v_mfma_f32_16x16x32_bf16 v[20:23], v[208:211], v[242:245], v[20:23]
	v_mfma_f32_16x16x32_bf16 v[16:19], v[218:221], v[242:245], v[16:19]
	v_mfma_f32_16x16x32_bf16 v[4:7], v[208:211], v[250:253], v[4:7]
	v_mfma_f32_16x16x32_bf16 v[0:3], v[218:221], v[250:253], v[0:3]
	s_setprio 0
	s_barrier
	s_add_u32 s6, s6, 0x100
	s_addc_u32 s7, s7, 0
	s_cmp_gt_u32 s14, 13
	s_mov_b32 s14, s15
	s_cbranch_scc0 .LBB0_124
	s_and_b64 vcc, exec, s[66:67]
	s_cbranch_vccz .LBB0_127
	s_barrier

.LBB0_504:
	s_add_u32 s20, s31, s44
	ds_read_b128 v[132:135], v217
	ds_read_b128 v[136:139], v217 offset:1024
	ds_read_b128 v[140:143], v217 offset:2048
	ds_read_b128 v[144:147], v217 offset:3072
	ds_read_b128 v[148:151], v218
	ds_read_b128 v[152:155], v218 offset:1024
	ds_read_b128 v[156:159], v218 offset:2048
	ds_read_b128 v[160:163], v218 offset:3072
	s_addc_u32 s48, s39, s45
	s_cmpk_eq_i32 s44, 0x700
	s_cselect_b64 s[46:47], -1, 0
	s_and_b64 s[46:47], s[46:47], exec
	s_cselect_b32 s47, s19, s48
	s_cselect_b32 s46, s29, s20
	s_add_i32 s64, s63, 2
	s_cmpk_eq_i32 s44, 0x700
	s_cselect_b64 s[48:49], -1, 0
	s_and_b64 s[66:67], s[48:49], exec
	s_cselect_b32 s20, 0, s64
	s_and_b64 s[48:49], s[48:49], s[6:7]
	s_and_b64 s[48:49], s[48:49], exec
	s_cselect_b32 s48, s35, s43
	s_cselect_b32 s49, s34, s42
	v_lshl_add_u64 v[238:239], v[128:129], 0, s[44:45]
	s_add_i32 m0, s50, 0xc000
	ds_read_b128 v[164:167], v219
	ds_read_b128 v[168:171], v219 offset:1024
	ds_read_b128 v[172:175], v219 offset:2048
	ds_read_b128 v[192:195], v219 offset:3072
	ds_read_b128 v[222:225], v219 offset:4096
	ds_read_b128 v[226:229], v219 offset:5120
	ds_read_b128 v[230:233], v219 offset:6144
	ds_read_b128 v[234:237], v219 offset:7168
	global_load_lds_dwordx4 v[238:239], off
	v_lshl_add_u64 v[238:239], v[130:131], 0, s[44:45]
	s_add_i32 m0, s50, 0xe000
	s_nop 0
	global_load_lds_dwordx4 v[238:239], off
	s_waitcnt vmcnt(8)
	s_waitcnt lgkmcnt(0)
	s_barrier
	s_setprio 1
	v_mfma_f32_16x16x32_bf16 v[124:127], v[132:135], v[164:167], v[124:127]
	v_mfma_f32_16x16x32_bf16 v[120:123], v[140:143], v[164:167], v[120:123]
	v_mfma_f32_16x16x32_bf16 v[108:111], v[132:135], v[172:175], v[108:111]
	v_mfma_f32_16x16x32_bf16 v[104:107], v[140:143], v[172:175], v[104:107]
	v_mfma_f32_16x16x32_bf16 v[92:95], v[132:135], v[222:225], v[92:95]
	v_mfma_f32_16x16x32_bf16 v[88:91], v[140:143], v[222:225], v[88:91]
	v_mfma_f32_16x16x32_bf16 v[76:79], v[132:135], v[230:233], v[76:79]
	v_mfma_f32_16x16x32_bf16 v[72:75], v[140:143], v[230:233], v[72:75]
	v_mfma_f32_16x16x32_bf16 v[124:127], v[136:139], v[168:171], v[124:127]
	v_mfma_f32_16x16x32_bf16 v[120:123], v[144:147], v[168:171], v[120:123]
	v_mfma_f32_16x16x32_bf16 v[108:111], v[136:139], v[192:195], v[108:111]
	v_mfma_f32_16x16x32_bf16 v[104:107], v[144:147], v[192:195], v[104:107]
	v_mfma_f32_16x16x32_bf16 v[92:95], v[136:139], v[226:229], v[92:95]
	v_mfma_f32_16x16x32_bf16 v[88:91], v[144:147], v[226:229], v[88:91]
	v_mfma_f32_16x16x32_bf16 v[76:79], v[136:139], v[234:237], v[76:79]
	v_mfma_f32_16x16x32_bf16 v[72:75], v[144:147], v[234:237], v[72:75]
	s_setprio 0
	s_setprio 1
	v_mfma_f32_16x16x32_bf16 v[116:119], v[148:151], v[164:167], v[116:119]
	v_mfma_f32_16x16x32_bf16 v[112:115], v[156:159], v[164:167], v[112:115]
	v_mfma_f32_16x16x32_bf16 v[100:103], v[148:151], v[172:175], v[100:103]
	v_mfma_f32_16x16x32_bf16 v[96:99], v[156:159], v[172:175], v[96:99]
	v_mfma_f32_16x16x32_bf16 v[84:87], v[148:151], v[222:225], v[84:87]
	v_mfma_f32_16x16x32_bf16 v[80:83], v[156:159], v[222:225], v[80:83]
	v_mfma_f32_16x16x32_bf16 v[68:71], v[148:151], v[230:233], v[68:71]
	v_mfma_f32_16x16x32_bf16 v[64:67], v[156:159], v[230:233], v[64:67]
	v_mfma_f32_16x16x32_bf16 v[116:119], v[152:155], v[168:171], v[116:119]
	v_mfma_f32_16x16x32_bf16 v[112:115], v[160:163], v[168:171], v[112:115]
	v_mfma_f32_16x16x32_bf16 v[100:103], v[152:155], v[192:195], v[100:103]
	v_mfma_f32_16x16x32_bf16 v[96:99], v[160:163], v[192:195], v[96:99]
	v_mfma_f32_16x16x32_bf16 v[84:87], v[152:155], v[226:229], v[84:87]
	v_mfma_f32_16x16x32_bf16 v[80:83], v[160:163], v[226:229], v[80:83]
	v_mfma_f32_16x16x32_bf16 v[68:71], v[152:155], v[234:237], v[68:71]
	v_mfma_f32_16x16x32_bf16 v[64:67], v[160:163], v[234:237], v[64:67]
	s_setprio 0
	s_barrier
	s_add_i32 s65, s58, s33
	v_lshl_add_u64 v[238:239], s[46:47], 0, v[178:179]
	s_mov_b32 m0, s65
	ds_read_b128 v[164:167], v219 offset:16384
	ds_read_b128 v[168:171], v219 offset:17408
	ds_read_b128 v[172:175], v219 offset:18432
	ds_read_b128 v[192:195], v219 offset:19456
	ds_read_b128 v[222:225], v219 offset:20480
	ds_read_b128 v[226:229], v219 offset:21504
	ds_read_b128 v[230:233], v219 offset:22528
	ds_read_b128 v[234:237], v219 offset:23552
	global_load_lds_dwordx4 v[238:239], off
	s_add_i32 m0, s65, 0x2000
	s_add_u32 s66, s46, 0x40000
	v_lshl_add_u64 v[240:241], s[46:47], 0, v[182:183]
	s_addc_u32 s67, s47, 0
	s_add_i32 s65, s59, s33
	global_load_lds_dwordx4 v[240:241], off
	v_lshl_add_u64 v[242:243], s[66:67], 0, v[178:179]
	s_mov_b32 m0, s65
	s_nop 0
	global_load_lds_dwordx4 v[242:243], off
	v_lshl_add_u64 v[242:243], s[66:67], 0, v[182:183]
	s_add_i32 m0, s65, 0x2000
	s_lshl_b64 s[66:67], s[20:21], 7
	s_add_u32 s66, s49, s66
	s_addc_u32 s67, s48, s67
	global_load_lds_dwordx4 v[242:243], off
	v_lshl_add_u64 v[242:243], s[66:67], 0, v[176:177]
	s_mov_b32 m0, s50
	s_nop 0
	global_load_lds_dwordx4 v[242:243], off
	v_lshl_add_u64 v[242:243], s[66:67], 0, v[180:181]
	s_mov_b32 m0, s51
	s_nop 0
	global_load_lds_dwordx4 v[242:243], off
	s_waitcnt vmcnt(8)
	s_waitcnt lgkmcnt(0)
	s_barrier
	s_setprio 1
	v_mfma_f32_16x16x32_bf16 v[60:63], v[132:135], v[164:167], v[60:63]
	v_mfma_f32_16x16x32_bf16 v[56:59], v[140:143], v[164:167], v[56:59]
	v_mfma_f32_16x16x32_bf16 v[44:47], v[132:135], v[172:175], v[44:47]
	v_mfma_f32_16x16x32_bf16 v[40:43], v[140:143], v[172:175], v[40:43]
	v_mfma_f32_16x16x32_bf16 v[28:31], v[132:135], v[222:225], v[28:31]
	v_mfma_f32_16x16x32_bf16 v[24:27], v[140:143], v[222:225], v[24:27]
	v_mfma_f32_16x16x32_bf16 v[12:15], v[132:135], v[230:233], v[12:15]
	v_mfma_f32_16x16x32_bf16 v[8:11], v[140:143], v[230:233], v[8:11]
	v_mfma_f32_16x16x32_bf16 v[60:63], v[136:139], v[168:171], v[60:63]
	v_mfma_f32_16x16x32_bf16 v[56:59], v[144:147], v[168:171], v[56:59]
	v_mfma_f32_16x16x32_bf16 v[44:47], v[136:139], v[192:195], v[44:47]
	v_mfma_f32_16x16x32_bf16 v[40:43], v[144:147], v[192:195], v[40:43]
	v_mfma_f32_16x16x32_bf16 v[28:31], v[136:139], v[226:229], v[28:31]
	v_mfma_f32_16x16x32_bf16 v[24:27], v[144:147], v[226:229], v[24:27]
	v_mfma_f32_16x16x32_bf16 v[12:15], v[136:139], v[234:237], v[12:15]
	v_mfma_f32_16x16x32_bf16 v[8:11], v[144:147], v[234:237], v[8:11]
	s_setprio 0
	s_setprio 1
	v_mfma_f32_16x16x32_bf16 v[52:55], v[148:151], v[164:167], v[52:55]
	v_mfma_f32_16x16x32_bf16 v[48:51], v[156:159], v[164:167], v[48:51]
	v_mfma_f32_16x16x32_bf16 v[36:39], v[148:151], v[172:175], v[36:39]
	v_mfma_f32_16x16x32_bf16 v[32:35], v[156:159], v[172:175], v[32:35]
	v_mfma_f32_16x16x32_bf16 v[20:23], v[148:151], v[222:225], v[20:23]
	v_mfma_f32_16x16x32_bf16 v[16:19], v[156:159], v[222:225], v[16:19]
	v_mfma_f32_16x16x32_bf16 v[4:7], v[148:151], v[230:233], v[4:7]
	v_mfma_f32_16x16x32_bf16 v[0:3], v[156:159], v[230:233], v[0:3]
	v_mfma_f32_16x16x32_bf16 v[52:55], v[152:155], v[168:171], v[52:55]
	v_mfma_f32_16x16x32_bf16 v[48:51], v[160:163], v[168:171], v[48:51]
	v_mfma_f32_16x16x32_bf16 v[36:39], v[152:155], v[192:195], v[36:39]
	v_mfma_f32_16x16x32_bf16 v[32:35], v[160:163], v[192:195], v[32:35]
	v_mfma_f32_16x16x32_bf16 v[20:23], v[152:155], v[226:229], v[20:23]
	v_mfma_f32_16x16x32_bf16 v[16:19], v[160:163], v[226:229], v[16:19]
	v_mfma_f32_16x16x32_bf16 v[4:7], v[152:155], v[234:237], v[4:7]
	v_mfma_f32_16x16x32_bf16 v[0:3], v[160:163], v[234:237], v[0:3]
	s_setprio 0
	s_barrier
	s_add_i32 s65, 0, 0x18000
	s_add_i32 s68, 0, 0x1c000
	v_add_u32_e32 v144, s65, v198
	v_add_u32_e32 v160, s68, v198
	ds_read_b128 v[132:135], v144
	ds_read_b128 v[136:139], v144 offset:1024
	ds_read_b128 v[140:143], v144 offset:2048
	ds_read_b128 v[144:147], v144 offset:3072
	ds_read_b128 v[148:151], v160
	ds_read_b128 v[152:155], v160 offset:1024
	ds_read_b128 v[156:159], v160 offset:2048
	ds_read_b128 v[160:163], v160 offset:3072
	s_add_u32 s66, s66, 0x40000
	s_addc_u32 s67, s67, 0
	s_mov_b32 m0, s52
	v_lshl_add_u64 v[242:243], s[66:67], 0, v[176:177]
	ds_read_b128 v[164:167], v219 offset:32768
	ds_read_b128 v[168:171], v219 offset:33792
	ds_read_b128 v[172:175], v219 offset:34816
	ds_read_b128 v[192:195], v219 offset:35840
	ds_read_b128 v[222:225], v219 offset:36864
	ds_read_b128 v[226:229], v219 offset:37888
	ds_read_b128 v[230:233], v219 offset:38912
	ds_read_b128 v[234:237], v219 offset:39936
	global_load_lds_dwordx4 v[242:243], off
	v_lshl_add_u64 v[242:243], s[66:67], 0, v[180:181]
	s_mov_b32 m0, s53
	s_nop 0
	global_load_lds_dwordx4 v[242:243], off
	s_waitcnt vmcnt(8)
	s_waitcnt lgkmcnt(0)
	s_barrier
	s_setprio 1
	v_mfma_f32_16x16x32_bf16 v[124:127], v[132:135], v[164:167], v[124:127]
	v_mfma_f32_16x16x32_bf16 v[120:123], v[140:143], v[164:167], v[120:123]
	v_mfma_f32_16x16x32_bf16 v[108:111], v[132:135], v[172:175], v[108:111]
	v_mfma_f32_16x16x32_bf16 v[104:107], v[140:143], v[172:175], v[104:107]
	v_mfma_f32_16x16x32_bf16 v[92:95], v[132:135], v[222:225], v[92:95]
	v_mfma_f32_16x16x32_bf16 v[88:91], v[140:143], v[222:225], v[88:91]
	v_mfma_f32_16x16x32_bf16 v[76:79], v[132:135], v[230:233], v[76:79]
	v_mfma_f32_16x16x32_bf16 v[72:75], v[140:143], v[230:233], v[72:75]
	v_mfma_f32_16x16x32_bf16 v[124:127], v[136:139], v[168:171], v[124:127]
	v_mfma_f32_16x16x32_bf16 v[120:123], v[144:147], v[168:171], v[120:123]
	v_mfma_f32_16x16x32_bf16 v[108:111], v[136:139], v[192:195], v[108:111]
	v_mfma_f32_16x16x32_bf16 v[104:107], v[144:147], v[192:195], v[104:107]
	v_mfma_f32_16x16x32_bf16 v[92:95], v[136:139], v[226:229], v[92:95]
	v_mfma_f32_16x16x32_bf16 v[88:91], v[144:147], v[226:229], v[88:91]
	v_mfma_f32_16x16x32_bf16 v[76:79], v[136:139], v[234:237], v[76:79]
	v_mfma_f32_16x16x32_bf16 v[72:75], v[144:147], v[234:237], v[72:75]
	s_setprio 0
	s_setprio 1
	v_mfma_f32_16x16x32_bf16 v[116:119], v[148:151], v[164:167], v[116:119]
	v_mfma_f32_16x16x32_bf16 v[112:115], v[156:159], v[164:167], v[112:115]
	v_mfma_f32_16x16x32_bf16 v[100:103], v[148:151], v[172:175], v[100:103]
	v_mfma_f32_16x16x32_bf16 v[96:99], v[156:159], v[172:175], v[96:99]
	v_mfma_f32_16x16x32_bf16 v[84:87], v[148:151], v[222:225], v[84:87]
	v_mfma_f32_16x16x32_bf16 v[80:83], v[156:159], v[222:225], v[80:83]
	v_mfma_f32_16x16x32_bf16 v[68:71], v[148:151], v[230:233], v[68:71]
	v_mfma_f32_16x16x32_bf16 v[64:67], v[156:159], v[230:233], v[64:67]
	v_mfma_f32_16x16x32_bf16 v[116:119], v[152:155], v[168:171], v[116:119]
	v_mfma_f32_16x16x32_bf16 v[112:115], v[160:163], v[168:171], v[112:115]
	v_mfma_f32_16x16x32_bf16 v[100:103], v[152:155], v[192:195], v[100:103]
	v_mfma_f32_16x16x32_bf16 v[96:99], v[160:163], v[192:195], v[96:99]
	v_mfma_f32_16x16x32_bf16 v[84:87], v[152:155], v[226:229], v[84:87]
	v_mfma_f32_16x16x32_bf16 v[80:83], v[160:163], v[226:229], v[80:83]
	v_mfma_f32_16x16x32_bf16 v[68:71], v[152:155], v[234:237], v[68:71]
	v_mfma_f32_16x16x32_bf16 v[64:67], v[160:163], v[234:237], v[64:67]
	s_setprio 0
	s_barrier
	s_add_i32 s65, s65, s33
	v_lshl_add_u64 v[238:239], v[238:239], 0, s[24:25]
	s_mov_b32 m0, s65
	ds_read_b128 v[164:167], v219 offset:49152
	ds_read_b128 v[168:171], v219 offset:50176
	ds_read_b128 v[172:175], v219 offset:51200
	ds_read_b128 v[192:195], v219 offset:52224
	ds_read_b128 v[222:225], v219 offset:53248
	ds_read_b128 v[226:229], v219 offset:54272
	ds_read_b128 v[230:233], v219 offset:55296
	ds_read_b128 v[234:237], v219 offset:56320
	global_load_lds_dwordx4 v[238:239], off
	s_add_i32 m0, s65, 0x2000
	s_add_u32 s46, s46, 0x40080
	v_lshl_add_u64 v[238:239], v[240:241], 0, s[24:25]
	s_addc_u32 s47, s47, 0
	s_add_i32 s65, s68, s33
	global_load_lds_dwordx4 v[238:239], off
	s_mov_b32 m0, s65
	s_or_b32 s20, s20, 1
	global_load_lds_dwordx4 v178, s[46:47]
	v_lshl_add_u64 v[238:239], s[46:47], 0, v[182:183]
	s_add_i32 m0, s65, 0x2000
	s_lshl_b64 s[46:47], s[20:21], 7
	s_add_u32 s46, s49, s46
	s_addc_u32 s47, s48, s47
	global_load_lds_dwordx4 v[238:239], off
	s_mov_b32 m0, s56
	s_nop 0
	global_load_lds_dwordx4 v176, s[46:47]
	s_mov_b32 m0, s57
	s_nop 0
	global_load_lds_dwordx4 v180, s[46:47]
	s_waitcnt vmcnt(8)
	s_waitcnt lgkmcnt(0)
	s_barrier
	s_setprio 1
	v_mfma_f32_16x16x32_bf16 v[60:63], v[132:135], v[164:167], v[60:63]
	v_mfma_f32_16x16x32_bf16 v[56:59], v[140:143], v[164:167], v[56:59]
	v_mfma_f32_16x16x32_bf16 v[44:47], v[132:135], v[172:175], v[44:47]
	v_mfma_f32_16x16x32_bf16 v[40:43], v[140:143], v[172:175], v[40:43]
	v_mfma_f32_16x16x32_bf16 v[28:31], v[132:135], v[222:225], v[28:31]
	v_mfma_f32_16x16x32_bf16 v[24:27], v[140:143], v[222:225], v[24:27]
	v_mfma_f32_16x16x32_bf16 v[12:15], v[132:135], v[230:233], v[12:15]
	v_mfma_f32_16x16x32_bf16 v[8:11], v[140:143], v[230:233], v[8:11]
	v_mfma_f32_16x16x32_bf16 v[60:63], v[136:139], v[168:171], v[60:63]
	v_mfma_f32_16x16x32_bf16 v[56:59], v[144:147], v[168:171], v[56:59]
	v_mfma_f32_16x16x32_bf16 v[44:47], v[136:139], v[192:195], v[44:47]
	v_mfma_f32_16x16x32_bf16 v[40:43], v[144:147], v[192:195], v[40:43]
	v_mfma_f32_16x16x32_bf16 v[28:31], v[136:139], v[226:229], v[28:31]
	v_mfma_f32_16x16x32_bf16 v[24:27], v[144:147], v[226:229], v[24:27]
	v_mfma_f32_16x16x32_bf16 v[12:15], v[136:139], v[234:237], v[12:15]
	v_mfma_f32_16x16x32_bf16 v[8:11], v[144:147], v[234:237], v[8:11]
	s_setprio 0
	s_setprio 1
	v_mfma_f32_16x16x32_bf16 v[52:55], v[148:151], v[164:167], v[52:55]
	v_mfma_f32_16x16x32_bf16 v[48:51], v[156:159], v[164:167], v[48:51]
	v_mfma_f32_16x16x32_bf16 v[36:39], v[148:151], v[172:175], v[36:39]
	v_mfma_f32_16x16x32_bf16 v[32:35], v[156:159], v[172:175], v[32:35]
	v_mfma_f32_16x16x32_bf16 v[20:23], v[148:151], v[222:225], v[20:23]
	v_mfma_f32_16x16x32_bf16 v[16:19], v[156:159], v[222:225], v[16:19]
	v_mfma_f32_16x16x32_bf16 v[4:7], v[148:151], v[230:233], v[4:7]
	v_mfma_f32_16x16x32_bf16 v[0:3], v[156:159], v[230:233], v[0:3]
	v_mfma_f32_16x16x32_bf16 v[52:55], v[152:155], v[168:171], v[52:55]
	v_mfma_f32_16x16x32_bf16 v[48:51], v[160:163], v[168:171], v[48:51]
	v_mfma_f32_16x16x32_bf16 v[36:39], v[152:155], v[192:195], v[36:39]
	v_mfma_f32_16x16x32_bf16 v[32:35], v[160:163], v[192:195], v[32:35]
	v_mfma_f32_16x16x32_bf16 v[20:23], v[152:155], v[226:229], v[20:23]
	v_mfma_f32_16x16x32_bf16 v[16:19], v[160:163], v[226:229], v[16:19]
	v_mfma_f32_16x16x32_bf16 v[4:7], v[152:155], v[234:237], v[4:7]
	v_mfma_f32_16x16x32_bf16 v[0:3], v[160:163], v[234:237], v[0:3]
	s_setprio 0
	s_barrier
	s_add_u32 s44, s44, 0x100
	s_addc_u32 s45, s45, 0
	s_cmp_gt_u32 s63, 13
	s_mov_b32 s63, s64
	s_cbranch_scc0 .LBB0_504
	s_and_b64 vcc, exec, s[26:27]
	s_cbranch_vccz .LBB0_507
	s_barrier

.LBB0_678:
	ds_read_b128 v[144:147], v193
	ds_read_b128 v[148:151], v193 offset:1024
	ds_read_b128 v[152:155], v193 offset:2048
	ds_read_b128 v[156:159], v193 offset:3072
	ds_read_b128 v[160:163], v194
	ds_read_b128 v[164:167], v194 offset:1024
	ds_read_b128 v[168:171], v194 offset:2048
	ds_read_b128 v[172:175], v194 offset:3072
	s_cmp_eq_u32 s22, 0x7e04000
	s_cselect_b64 s[24:25], -1, 0
	s_and_b64 s[24:25], s[24:25], exec
	s_cselect_b32 s25, s9, s43
	s_cselect_b32 s24, s11, s42
	s_add_i32 s45, s44, 2
	s_cmp_eq_u32 s22, 0x7e04000
	s_cselect_b64 s[26:27], -1, 0
	s_and_b64 s[46:47], s[26:27], exec
	s_cselect_b32 s6, 0, s45
	s_and_b64 s[26:27], s[26:27], s[4:5]
	s_and_b64 s[26:27], s[26:27], exec
	s_cselect_b32 s26, s15, s21
	s_cselect_b32 s27, s14, s20
	v_lshl_add_u64 v[188:189], v[140:141], 0, s[22:23]
	s_add_i32 m0, s19, 0xc000
	ds_read_b128 v[176:179], v195
	ds_read_b128 v[180:183], v195 offset:1024
	ds_read_b128 v[184:187], v195 offset:2048
	ds_read_b128 v[196:199], v195 offset:3072
	ds_read_b128 v[200:203], v195 offset:4096
	ds_read_b128 v[204:207], v195 offset:5120
	ds_read_b128 v[208:211], v195 offset:6144
	ds_read_b128 v[212:215], v195 offset:7168
	global_load_lds_dwordx4 v[188:189], off
	v_lshl_add_u64 v[188:189], v[142:143], 0, s[22:23]
	s_add_i32 m0, s19, 0xe000
	s_nop 0
	global_load_lds_dwordx4 v[188:189], off
	s_waitcnt vmcnt(8)
	s_waitcnt lgkmcnt(0)
	s_barrier
	s_setprio 1
	v_mfma_f32_16x16x32_bf16 v[124:127], v[144:147], v[176:179], v[124:127]
	v_mfma_f32_16x16x32_bf16 v[120:123], v[152:155], v[176:179], v[120:123]
	v_mfma_f32_16x16x32_bf16 v[112:115], v[144:147], v[184:187], v[112:115]
	v_mfma_f32_16x16x32_bf16 v[104:107], v[152:155], v[184:187], v[104:107]
	v_mfma_f32_16x16x32_bf16 v[96:99], v[144:147], v[200:203], v[96:99]
	v_mfma_f32_16x16x32_bf16 v[88:91], v[152:155], v[200:203], v[88:91]
	v_mfma_f32_16x16x32_bf16 v[80:83], v[144:147], v[208:211], v[80:83]
	v_mfma_f32_16x16x32_bf16 v[72:75], v[152:155], v[208:211], v[72:75]
	v_mfma_f32_16x16x32_bf16 v[124:127], v[148:151], v[180:183], v[124:127]
	v_mfma_f32_16x16x32_bf16 v[120:123], v[156:159], v[180:183], v[120:123]
	v_mfma_f32_16x16x32_bf16 v[112:115], v[148:151], v[196:199], v[112:115]
	v_mfma_f32_16x16x32_bf16 v[104:107], v[156:159], v[196:199], v[104:107]
	v_mfma_f32_16x16x32_bf16 v[96:99], v[148:151], v[204:207], v[96:99]
	v_mfma_f32_16x16x32_bf16 v[88:91], v[156:159], v[204:207], v[88:91]
	v_mfma_f32_16x16x32_bf16 v[80:83], v[148:151], v[212:215], v[80:83]
	v_mfma_f32_16x16x32_bf16 v[72:75], v[156:159], v[212:215], v[72:75]
	s_setprio 0
	s_setprio 1
	v_mfma_f32_16x16x32_bf16 v[116:119], v[160:163], v[176:179], v[116:119]
	v_mfma_f32_16x16x32_bf16 v[108:111], v[168:171], v[176:179], v[108:111]
	v_mfma_f32_16x16x32_bf16 v[100:103], v[160:163], v[184:187], v[100:103]
	v_mfma_f32_16x16x32_bf16 v[92:95], v[168:171], v[184:187], v[92:95]
	v_mfma_f32_16x16x32_bf16 v[84:87], v[160:163], v[200:203], v[84:87]
	v_mfma_f32_16x16x32_bf16 v[76:79], v[168:171], v[200:203], v[76:79]
	v_mfma_f32_16x16x32_bf16 v[68:71], v[160:163], v[208:211], v[68:71]
	v_mfma_f32_16x16x32_bf16 v[64:67], v[168:171], v[208:211], v[64:67]
	v_mfma_f32_16x16x32_bf16 v[116:119], v[164:167], v[180:183], v[116:119]
	v_mfma_f32_16x16x32_bf16 v[108:111], v[172:175], v[180:183], v[108:111]
	v_mfma_f32_16x16x32_bf16 v[100:103], v[164:167], v[196:199], v[100:103]
	v_mfma_f32_16x16x32_bf16 v[92:95], v[172:175], v[196:199], v[92:95]
	v_mfma_f32_16x16x32_bf16 v[84:87], v[164:167], v[204:207], v[84:87]
	v_mfma_f32_16x16x32_bf16 v[76:79], v[172:175], v[204:207], v[76:79]
	v_mfma_f32_16x16x32_bf16 v[68:71], v[164:167], v[212:215], v[68:71]
	v_mfma_f32_16x16x32_bf16 v[64:67], v[172:175], v[212:215], v[64:67]
	s_setprio 0
	s_barrier
	s_add_i32 s46, s38, s29
	v_lshl_add_u64 v[188:189], s[24:25], 0, v[128:129]
	s_mov_b32 m0, s46
	ds_read_b128 v[176:179], v195 offset:16384
	ds_read_b128 v[180:183], v195 offset:17408
	ds_read_b128 v[184:187], v195 offset:18432
	ds_read_b128 v[196:199], v195 offset:19456
	ds_read_b128 v[200:203], v195 offset:20480
	ds_read_b128 v[204:207], v195 offset:21504
	ds_read_b128 v[208:211], v195 offset:22528
	ds_read_b128 v[212:215], v195 offset:23552
	global_load_lds_dwordx4 v[188:189], off
	s_add_i32 m0, s46, 0x2000
	s_add_u32 s46, s24, 0x4000
	s_addc_u32 s47, s25, 0
	s_add_i32 s48, s39, s29
	global_load_lds_dwordx4 v130, s[24:25]
	s_mov_b32 m0, s48
	s_nop 0
	global_load_lds_dwordx4 v128, s[46:47]
	v_lshl_add_u64 v[188:189], s[46:47], 0, v[130:131]
	s_add_i32 m0, s48, 0x2000
	s_lshl_b64 s[46:47], s[6:7], 21
	s_add_u32 s46, s27, s46
	s_addc_u32 s47, s26, s47
	global_load_lds_dwordx4 v[188:189], off
	s_mov_b32 m0, s19
	s_nop 0
	global_load_lds_dwordx4 v128, s[46:47]
	s_mov_b32 m0, s31
	s_nop 0
	global_load_lds_dwordx4 v130, s[46:47]
	s_waitcnt vmcnt(8)
	s_waitcnt lgkmcnt(0)
	s_barrier
	s_setprio 1
	v_mfma_f32_16x16x32_bf16 v[60:63], v[144:147], v[176:179], v[60:63]
	v_mfma_f32_16x16x32_bf16 v[56:59], v[152:155], v[176:179], v[56:59]
	v_mfma_f32_16x16x32_bf16 v[48:51], v[144:147], v[184:187], v[48:51]
	v_mfma_f32_16x16x32_bf16 v[40:43], v[152:155], v[184:187], v[40:43]
	v_mfma_f32_16x16x32_bf16 v[32:35], v[144:147], v[200:203], v[32:35]
	v_mfma_f32_16x16x32_bf16 v[24:27], v[152:155], v[200:203], v[24:27]
	v_mfma_f32_16x16x32_bf16 v[16:19], v[144:147], v[208:211], v[16:19]
	v_mfma_f32_16x16x32_bf16 v[8:11], v[152:155], v[208:211], v[8:11]
	v_mfma_f32_16x16x32_bf16 v[60:63], v[148:151], v[180:183], v[60:63]
	v_mfma_f32_16x16x32_bf16 v[56:59], v[156:159], v[180:183], v[56:59]
	v_mfma_f32_16x16x32_bf16 v[48:51], v[148:151], v[196:199], v[48:51]
	v_mfma_f32_16x16x32_bf16 v[40:43], v[156:159], v[196:199], v[40:43]
	v_mfma_f32_16x16x32_bf16 v[32:35], v[148:151], v[204:207], v[32:35]
	v_mfma_f32_16x16x32_bf16 v[24:27], v[156:159], v[204:207], v[24:27]
	v_mfma_f32_16x16x32_bf16 v[16:19], v[148:151], v[212:215], v[16:19]
	v_mfma_f32_16x16x32_bf16 v[8:11], v[156:159], v[212:215], v[8:11]
	s_setprio 0
	s_setprio 1
	v_mfma_f32_16x16x32_bf16 v[52:55], v[160:163], v[176:179], v[52:55]
	v_mfma_f32_16x16x32_bf16 v[44:47], v[168:171], v[176:179], v[44:47]
	v_mfma_f32_16x16x32_bf16 v[36:39], v[160:163], v[184:187], v[36:39]
	v_mfma_f32_16x16x32_bf16 v[28:31], v[168:171], v[184:187], v[28:31]
	v_mfma_f32_16x16x32_bf16 v[20:23], v[160:163], v[200:203], v[20:23]
	v_mfma_f32_16x16x32_bf16 v[12:15], v[168:171], v[200:203], v[12:15]
	v_mfma_f32_16x16x32_bf16 v[4:7], v[160:163], v[208:211], v[4:7]
	v_mfma_f32_16x16x32_bf16 v[0:3], v[168:171], v[208:211], v[0:3]
	v_mfma_f32_16x16x32_bf16 v[52:55], v[164:167], v[180:183], v[52:55]
	v_mfma_f32_16x16x32_bf16 v[44:47], v[172:175], v[180:183], v[44:47]
	v_mfma_f32_16x16x32_bf16 v[36:39], v[164:167], v[196:199], v[36:39]
	v_mfma_f32_16x16x32_bf16 v[28:31], v[172:175], v[196:199], v[28:31]
	v_mfma_f32_16x16x32_bf16 v[20:23], v[164:167], v[204:207], v[20:23]
	v_mfma_f32_16x16x32_bf16 v[12:15], v[172:175], v[204:207], v[12:15]
	v_mfma_f32_16x16x32_bf16 v[4:7], v[164:167], v[212:215], v[4:7]
	v_mfma_f32_16x16x32_bf16 v[0:3], v[172:175], v[212:215], v[0:3]
	s_setprio 0
	s_barrier
	s_add_i32 s48, 0, 0x18000
	s_add_i32 s49, 0, 0x1c000
	v_add_u32_e32 v156, s48, v191
	v_add_u32_e32 v172, s49, v191
	ds_read_b128 v[144:147], v156
	ds_read_b128 v[148:151], v156 offset:1024
	ds_read_b128 v[152:155], v156 offset:2048
	ds_read_b128 v[156:159], v156 offset:3072
	ds_read_b128 v[160:163], v172
	ds_read_b128 v[164:167], v172 offset:1024
	ds_read_b128 v[168:171], v172 offset:2048
	ds_read_b128 v[172:175], v172 offset:3072
	s_add_u32 s46, s46, 0x4000
	s_addc_u32 s47, s47, 0
	s_mov_b32 m0, s33
	ds_read_b128 v[176:179], v195 offset:32768
	ds_read_b128 v[180:183], v195 offset:33792
	ds_read_b128 v[184:187], v195 offset:34816
	ds_read_b128 v[196:199], v195 offset:35840
	ds_read_b128 v[200:203], v195 offset:36864
	ds_read_b128 v[204:207], v195 offset:37888
	ds_read_b128 v[208:211], v195 offset:38912
	ds_read_b128 v[212:215], v195 offset:39936
	global_load_lds_dwordx4 v128, s[46:47]
	s_mov_b32 m0, s34
	s_nop 0
	global_load_lds_dwordx4 v130, s[46:47]
	s_waitcnt vmcnt(8)
	s_waitcnt lgkmcnt(0)
	s_barrier
	s_setprio 1
	v_mfma_f32_16x16x32_bf16 v[124:127], v[144:147], v[176:179], v[124:127]
	v_mfma_f32_16x16x32_bf16 v[120:123], v[152:155], v[176:179], v[120:123]
	v_mfma_f32_16x16x32_bf16 v[112:115], v[144:147], v[184:187], v[112:115]
	v_mfma_f32_16x16x32_bf16 v[104:107], v[152:155], v[184:187], v[104:107]
	v_mfma_f32_16x16x32_bf16 v[96:99], v[144:147], v[200:203], v[96:99]
	v_mfma_f32_16x16x32_bf16 v[88:91], v[152:155], v[200:203], v[88:91]
	v_mfma_f32_16x16x32_bf16 v[80:83], v[144:147], v[208:211], v[80:83]
	v_mfma_f32_16x16x32_bf16 v[72:75], v[152:155], v[208:211], v[72:75]
	v_mfma_f32_16x16x32_bf16 v[124:127], v[148:151], v[180:183], v[124:127]
	v_mfma_f32_16x16x32_bf16 v[120:123], v[156:159], v[180:183], v[120:123]
	v_mfma_f32_16x16x32_bf16 v[112:115], v[148:151], v[196:199], v[112:115]
	v_mfma_f32_16x16x32_bf16 v[104:107], v[156:159], v[196:199], v[104:107]
	v_mfma_f32_16x16x32_bf16 v[96:99], v[148:151], v[204:207], v[96:99]
	v_mfma_f32_16x16x32_bf16 v[88:91], v[156:159], v[204:207], v[88:91]
	v_mfma_f32_16x16x32_bf16 v[80:83], v[148:151], v[212:215], v[80:83]
	v_mfma_f32_16x16x32_bf16 v[72:75], v[156:159], v[212:215], v[72:75]
	s_setprio 0
	s_setprio 1
	v_mfma_f32_16x16x32_bf16 v[116:119], v[160:163], v[176:179], v[116:119]
	v_mfma_f32_16x16x32_bf16 v[108:111], v[168:171], v[176:179], v[108:111]
	v_mfma_f32_16x16x32_bf16 v[100:103], v[160:163], v[184:187], v[100:103]
	v_mfma_f32_16x16x32_bf16 v[92:95], v[168:171], v[184:187], v[92:95]
	v_mfma_f32_16x16x32_bf16 v[84:87], v[160:163], v[200:203], v[84:87]
	v_mfma_f32_16x16x32_bf16 v[76:79], v[168:171], v[200:203], v[76:79]
	v_mfma_f32_16x16x32_bf16 v[68:71], v[160:163], v[208:211], v[68:71]
	v_mfma_f32_16x16x32_bf16 v[64:67], v[168:171], v[208:211], v[64:67]
	v_mfma_f32_16x16x32_bf16 v[116:119], v[164:167], v[180:183], v[116:119]
	v_mfma_f32_16x16x32_bf16 v[108:111], v[172:175], v[180:183], v[108:111]
	v_mfma_f32_16x16x32_bf16 v[100:103], v[164:167], v[196:199], v[100:103]
	v_mfma_f32_16x16x32_bf16 v[92:95], v[172:175], v[196:199], v[92:95]
	v_mfma_f32_16x16x32_bf16 v[84:87], v[164:167], v[204:207], v[84:87]
	v_mfma_f32_16x16x32_bf16 v[76:79], v[172:175], v[204:207], v[76:79]
	v_mfma_f32_16x16x32_bf16 v[68:71], v[164:167], v[212:215], v[68:71]
	v_mfma_f32_16x16x32_bf16 v[64:67], v[172:175], v[212:215], v[64:67]
	s_setprio 0
	s_barrier
	s_add_u32 s46, s24, 0x20000
	s_addc_u32 s47, s25, 0
	s_add_i32 s48, s48, s29
	v_lshl_add_u64 v[188:189], s[46:47], 0, v[128:129]
	s_mov_b32 m0, s48
	ds_read_b128 v[176:179], v195 offset:49152
	ds_read_b128 v[180:183], v195 offset:50176
	ds_read_b128 v[184:187], v195 offset:51200
	ds_read_b128 v[196:199], v195 offset:52224
	ds_read_b128 v[200:203], v195 offset:53248
	ds_read_b128 v[204:207], v195 offset:54272
	ds_read_b128 v[208:211], v195 offset:55296
	ds_read_b128 v[212:215], v195 offset:56320
	global_load_lds_dwordx4 v[188:189], off
	s_add_i32 m0, s48, 0x2000
	s_add_u32 s24, s24, 0x24000
	v_lshl_add_u64 v[188:189], s[46:47], 0, v[130:131]
	s_addc_u32 s25, s25, 0
	s_add_i32 s46, s49, s29
	global_load_lds_dwordx4 v[188:189], off
	s_mov_b32 m0, s46
	s_or_b32 s6, s6, 1
	global_load_lds_dwordx4 v128, s[24:25]
	v_lshl_add_u64 v[188:189], s[24:25], 0, v[130:131]
	s_add_i32 m0, s46, 0x2000
	s_lshl_b64 s[24:25], s[6:7], 21
	s_add_u32 s24, s27, s24
	s_addc_u32 s25, s26, s25
	global_load_lds_dwordx4 v[188:189], off
	s_mov_b32 m0, s36
	s_nop 0
	global_load_lds_dwordx4 v128, s[24:25]
	s_mov_b32 m0, s37
	s_nop 0
	global_load_lds_dwordx4 v130, s[24:25]
	s_waitcnt vmcnt(8)
	s_waitcnt lgkmcnt(0)
	s_barrier
	s_setprio 1
	v_mfma_f32_16x16x32_bf16 v[60:63], v[144:147], v[176:179], v[60:63]
	v_mfma_f32_16x16x32_bf16 v[56:59], v[152:155], v[176:179], v[56:59]
	v_mfma_f32_16x16x32_bf16 v[48:51], v[144:147], v[184:187], v[48:51]
	v_mfma_f32_16x16x32_bf16 v[40:43], v[152:155], v[184:187], v[40:43]
	v_mfma_f32_16x16x32_bf16 v[32:35], v[144:147], v[200:203], v[32:35]
	v_mfma_f32_16x16x32_bf16 v[24:27], v[152:155], v[200:203], v[24:27]
	v_mfma_f32_16x16x32_bf16 v[16:19], v[144:147], v[208:211], v[16:19]
	v_mfma_f32_16x16x32_bf16 v[8:11], v[152:155], v[208:211], v[8:11]
	v_mfma_f32_16x16x32_bf16 v[60:63], v[148:151], v[180:183], v[60:63]
	v_mfma_f32_16x16x32_bf16 v[56:59], v[156:159], v[180:183], v[56:59]
	v_mfma_f32_16x16x32_bf16 v[48:51], v[148:151], v[196:199], v[48:51]
	v_mfma_f32_16x16x32_bf16 v[40:43], v[156:159], v[196:199], v[40:43]
	v_mfma_f32_16x16x32_bf16 v[32:35], v[148:151], v[204:207], v[32:35]
	v_mfma_f32_16x16x32_bf16 v[24:27], v[156:159], v[204:207], v[24:27]
	v_mfma_f32_16x16x32_bf16 v[16:19], v[148:151], v[212:215], v[16:19]
	v_mfma_f32_16x16x32_bf16 v[8:11], v[156:159], v[212:215], v[8:11]
	s_setprio 0
	s_setprio 1
	v_mfma_f32_16x16x32_bf16 v[52:55], v[160:163], v[176:179], v[52:55]
	v_mfma_f32_16x16x32_bf16 v[44:47], v[168:171], v[176:179], v[44:47]
	v_mfma_f32_16x16x32_bf16 v[36:39], v[160:163], v[184:187], v[36:39]
	v_mfma_f32_16x16x32_bf16 v[28:31], v[168:171], v[184:187], v[28:31]
	v_mfma_f32_16x16x32_bf16 v[20:23], v[160:163], v[200:203], v[20:23]
	v_mfma_f32_16x16x32_bf16 v[12:15], v[168:171], v[200:203], v[12:15]
	v_mfma_f32_16x16x32_bf16 v[4:7], v[160:163], v[208:211], v[4:7]
	v_mfma_f32_16x16x32_bf16 v[0:3], v[168:171], v[208:211], v[0:3]
	v_mfma_f32_16x16x32_bf16 v[52:55], v[164:167], v[180:183], v[52:55]
	v_mfma_f32_16x16x32_bf16 v[44:47], v[172:175], v[180:183], v[44:47]
	v_mfma_f32_16x16x32_bf16 v[36:39], v[164:167], v[196:199], v[36:39]
	v_mfma_f32_16x16x32_bf16 v[28:31], v[172:175], v[196:199], v[28:31]
	v_mfma_f32_16x16x32_bf16 v[20:23], v[164:167], v[204:207], v[20:23]
	v_mfma_f32_16x16x32_bf16 v[12:15], v[172:175], v[204:207], v[12:15]
	v_mfma_f32_16x16x32_bf16 v[4:7], v[164:167], v[212:215], v[4:7]
	v_mfma_f32_16x16x32_bf16 v[0:3], v[172:175], v[212:215], v[0:3]
	s_setprio 0
	s_barrier
	s_add_u32 s22, s22, 0x400000
	s_addc_u32 s23, s23, 0
	s_add_u32 s42, s42, 0x40000
	s_addc_u32 s43, s43, 0
	s_cmp_gt_u32 s44, 61
	s_mov_b32 s44, s45
	s_cbranch_scc0 .LBB0_678
	v_lshl_or_b32 v142, s41, 8, v192
	v_lshl_add_u32 v144, s18, 8, v190
	v_ashrrev_i32_e32 v143, 31, v142
	v_ashrrev_i32_e32 v145, 31, v144
	v_lshl_add_u64 v[146:147], v[142:143], 1, s[12:13]
	v_lshlrev_b64 v[140:141], 11, v[144:145]
	v_lshl_add_u64 v[140:141], v[146:147], 0, v[140:141]
	global_load_dwordx2 v[196:197], v[140:141], off
	global_load_dwordx2 v[198:199], v[140:141], off offset:32
	global_load_dwordx2 v[200:201], v[140:141], off offset:256
	v_or_b32_e32 v202, 16, v144
	v_ashrrev_i32_e32 v203, 31, v202
	global_load_dwordx2 v[204:205], v[140:141], off offset:288
	v_lshlrev_b64 v[140:141], 11, v[202:203]
	v_lshl_add_u64 v[148:149], v[146:147], 0, v[140:141]
	global_load_dwordx2 v[206:207], v[148:149], off
	global_load_dwordx2 v[208:209], v[148:149], off offset:32
	global_load_dwordx2 v[210:211], v[148:149], off offset:256
	global_load_dwordx2 v[212:213], v[148:149], off offset:288
	v_or_b32_e32 v188, 32, v144
	v_or_b32_e32 v178, 48, v144
	v_add_u32_e32 v168, 0x80, v144
	v_add_u32_e32 v160, 0x90, v144
	v_add_u32_e32 v150, 0xa0, v144
	v_add_u32_e32 v140, 0xb0, v144
	v_ashrrev_i32_e32 v189, 31, v188
	v_ashrrev_i32_e32 v179, 31, v178
	v_ashrrev_i32_e32 v169, 31, v168
	v_ashrrev_i32_e32 v161, 31, v160
	v_ashrrev_i32_e32 v151, 31, v150
	v_ashrrev_i32_e32 v141, 31, v140
	v_lshlrev_b64 v[152:153], 12, v[144:145]
	v_lshlrev_b64 v[144:145], 2, v[142:143]
	v_lshlrev_b64 v[142:143], 11, v[188:189]
	v_lshlrev_b64 v[154:155], 11, v[178:179]
	v_lshlrev_b64 v[156:157], 11, v[168:169]
	v_lshlrev_b64 v[158:159], 11, v[160:161]
	v_lshlrev_b64 v[162:163], 11, v[150:151]
	v_lshlrev_b64 v[164:165], 11, v[140:141]
	v_lshl_add_u64 v[152:153], s[78:79], 0, v[152:153]
	v_lshl_add_u64 v[142:143], v[146:147], 0, v[142:143]
	v_lshl_add_u64 v[154:155], v[146:147], 0, v[154:155]
	v_lshl_add_u64 v[156:157], v[146:147], 0, v[156:157]
	v_lshl_add_u64 v[158:159], v[146:147], 0, v[158:159]
	v_lshl_add_u64 v[148:149], v[146:147], 0, v[162:163]
	v_lshl_add_u64 v[214:215], v[146:147], 0, v[164:165]
	v_lshl_add_u64 v[216:217], v[152:153], 0, v[144:145]
	global_load_dwordx2 v[218:219], v[142:143], off
	global_load_dwordx2 v[220:221], v[142:143], off offset:32
	global_load_dwordx2 v[222:223], v[142:143], off offset:256
	global_load_dwordx2 v[224:225], v[142:143], off offset:288
	global_load_dwordx2 v[226:227], v[154:155], off
	global_load_dwordx2 v[228:229], v[154:155], off offset:32
	global_load_dwordx2 v[186:187], v[154:155], off offset:256
	global_load_dwordx2 v[184:185], v[154:155], off offset:288
	global_load_dwordx2 v[182:183], v[156:157], off
	global_load_dwordx2 v[180:181], v[156:157], off offset:32
	global_load_dwordx2 v[176:177], v[156:157], off offset:256
	global_load_dwordx2 v[174:175], v[156:157], off offset:288
	global_load_dwordx2 v[172:173], v[158:159], off
	global_load_dwordx2 v[170:171], v[158:159], off offset:32
	global_load_dwordx2 v[166:167], v[158:159], off offset:256
	global_load_dwordx2 v[164:165], v[158:159], off offset:288
	global_load_dwordx2 v[162:163], v[148:149], off
	s_nop 0
	global_load_dwordx2 v[158:159], v[148:149], off offset:32
	global_load_dwordx2 v[156:157], v[148:149], off offset:256
	global_load_dwordx2 v[154:155], v[148:149], off offset:288
	global_load_dwordx2 v[152:153], v[214:215], off
	s_nop 0
	global_load_dwordx2 v[148:149], v[214:215], off offset:32
	global_load_dwordx2 v[146:147], v[214:215], off offset:256
	global_load_dwordx2 v[142:143], v[214:215], off offset:288
	s_and_b64 vcc, exec, s[0:1]
	s_mov_b32 s41, s8
	s_mov_b32 s18, s10
	s_mov_b64 s[22:23], s[16:17]
	s_mov_b64 s[20:21], s[14:15]
	s_waitcnt vmcnt(0)
	v_lshlrev_b32_e32 v214, 16, v196
	v_and_b32_e32 v215, 0xffff0000, v196
	v_lshlrev_b32_e32 v196, 16, v197
	v_and_b32_e32 v197, 0xffff0000, v197
	v_lshlrev_b32_e32 v230, 16, v198
	v_and_b32_e32 v231, 0xffff0000, v198
	v_lshlrev_b32_e32 v198, 16, v199
	v_and_b32_e32 v199, 0xffff0000, v199
	v_pk_add_f32 v[126:127], v[126:127], v[196:197]
	v_pk_add_f32 v[124:125], v[124:125], v[214:215]
	v_pk_add_f32 v[120:121], v[120:121], v[230:231]
	v_lshlrev_b32_e32 v232, 16, v200
	v_and_b32_e32 v233, 0xffff0000, v200
	v_pk_add_f32 v[122:123], v[122:123], v[198:199]
	global_store_dwordx4 v[216:217], v[124:127], off
	global_store_dwordx4 v[216:217], v[120:123], off offset:64
	v_pk_add_f32 v[116:117], v[116:117], v[232:233]
	s_nop 0
	v_lshlrev_b32_e32 v120, 16, v201
	v_and_b32_e32 v121, 0xffff0000, v201
	v_pk_add_f32 v[118:119], v[118:119], v[120:121]
	global_store_dwordx4 v[216:217], v[116:119], off offset:512
	s_nop 1
	v_lshlrev_b32_e32 v116, 16, v204
	v_and_b32_e32 v117, 0xffff0000, v204
	v_lshlrev_b32_e32 v118, 16, v205
	v_and_b32_e32 v119, 0xffff0000, v205
	v_pk_add_f32 v[110:111], v[110:111], v[118:119]
	v_pk_add_f32 v[108:109], v[108:109], v[116:117]
	global_store_dwordx4 v[216:217], v[108:111], off offset:576
	v_lshlrev_b64 v[116:117], 12, v[202:203]
	s_nop 0
	v_lshlrev_b32_e32 v108, 16, v206
	v_and_b32_e32 v109, 0xffff0000, v206
	v_lshlrev_b32_e32 v110, 16, v207
	v_and_b32_e32 v111, 0xffff0000, v207
	v_pk_add_f32 v[108:109], v[112:113], v[108:109]
	v_lshl_add_u64 v[112:113], s[78:79], 0, v[116:117]
	v_pk_add_f32 v[110:111], v[114:115], v[110:111]
	v_lshl_add_u64 v[112:113], v[112:113], 0, v[144:145]
	global_store_dwordx4 v[112:113], v[108:111], off
	s_nop 1
	v_lshlrev_b32_e32 v108, 16, v208
	v_and_b32_e32 v109, 0xffff0000, v208
	v_lshlrev_b32_e32 v110, 16, v209
	v_and_b32_e32 v111, 0xffff0000, v209
	v_pk_add_f32 v[106:107], v[106:107], v[110:111]
	v_pk_add_f32 v[104:105], v[104:105], v[108:109]
	global_store_dwordx4 v[112:113], v[104:107], off offset:64
	s_nop 1
	v_lshlrev_b32_e32 v104, 16, v210
	v_and_b32_e32 v105, 0xffff0000, v210
	v_lshlrev_b32_e32 v106, 16, v211
	v_and_b32_e32 v107, 0xffff0000, v211
	v_pk_add_f32 v[102:103], v[102:103], v[106:107]
	v_pk_add_f32 v[100:101], v[100:101], v[104:105]
	global_store_dwordx4 v[112:113], v[100:103], off offset:512
	s_nop 1
	v_lshlrev_b32_e32 v100, 16, v212
	v_and_b32_e32 v101, 0xffff0000, v212
	v_lshlrev_b32_e32 v102, 16, v213
	v_and_b32_e32 v103, 0xffff0000, v213
	v_pk_add_f32 v[94:95], v[94:95], v[102:103]
	v_pk_add_f32 v[92:93], v[92:93], v[100:101]
	global_store_dwordx4 v[112:113], v[92:95], off offset:576
	v_lshlrev_b64 v[100:101], 12, v[188:189]
	s_nop 0
	v_lshlrev_b32_e32 v92, 16, v218
	v_and_b32_e32 v93, 0xffff0000, v218
	v_lshlrev_b32_e32 v94, 16, v219
	v_and_b32_e32 v95, 0xffff0000, v219
	v_pk_add_f32 v[92:93], v[96:97], v[92:93]
	v_lshl_add_u64 v[96:97], s[78:79], 0, v[100:101]
	v_pk_add_f32 v[94:95], v[98:99], v[94:95]
	v_lshl_add_u64 v[96:97], v[96:97], 0, v[144:145]
	global_store_dwordx4 v[96:97], v[92:95], off
	s_nop 1
	v_lshlrev_b32_e32 v92, 16, v220
	v_and_b32_e32 v93, 0xffff0000, v220
	v_lshlrev_b32_e32 v94, 16, v221
	v_and_b32_e32 v95, 0xffff0000, v221
	v_pk_add_f32 v[90:91], v[90:91], v[94:95]
	v_pk_add_f32 v[88:89], v[88:89], v[92:93]
	global_store_dwordx4 v[96:97], v[88:91], off offset:64
	s_nop 1
	v_lshlrev_b32_e32 v88, 16, v222
	v_and_b32_e32 v89, 0xffff0000, v222
	v_lshlrev_b32_e32 v90, 16, v223
	v_and_b32_e32 v91, 0xffff0000, v223
	v_pk_add_f32 v[86:87], v[86:87], v[90:91]
	v_pk_add_f32 v[84:85], v[84:85], v[88:89]
	global_store_dwordx4 v[96:97], v[84:87], off offset:512
	s_nop 1
	v_lshlrev_b32_e32 v84, 16, v224
	v_and_b32_e32 v85, 0xffff0000, v224
	v_lshlrev_b32_e32 v86, 16, v225
	v_and_b32_e32 v87, 0xffff0000, v225
	v_pk_add_f32 v[78:79], v[78:79], v[86:87]
	v_pk_add_f32 v[76:77], v[76:77], v[84:85]
	global_store_dwordx4 v[96:97], v[76:79], off offset:576
	v_lshlrev_b64 v[84:85], 12, v[178:179]
	s_nop 0
	v_lshlrev_b32_e32 v76, 16, v226
	v_and_b32_e32 v77, 0xffff0000, v226
	v_lshlrev_b32_e32 v78, 16, v227
	v_and_b32_e32 v79, 0xffff0000, v227
	v_pk_add_f32 v[76:77], v[80:81], v[76:77]
	v_lshl_add_u64 v[80:81], s[78:79], 0, v[84:85]
	v_pk_add_f32 v[78:79], v[82:83], v[78:79]
	v_lshl_add_u64 v[80:81], v[80:81], 0, v[144:145]
	global_store_dwordx4 v[80:81], v[76:79], off
	s_nop 1
	v_lshlrev_b32_e32 v76, 16, v228
	v_and_b32_e32 v77, 0xffff0000, v228
	v_lshlrev_b32_e32 v78, 16, v229
	v_and_b32_e32 v79, 0xffff0000, v229
	v_pk_add_f32 v[74:75], v[74:75], v[78:79]
	v_pk_add_f32 v[72:73], v[72:73], v[76:77]
	global_store_dwordx4 v[80:81], v[72:75], off offset:64
	s_nop 1
	v_lshlrev_b32_e32 v72, 16, v186
	v_and_b32_e32 v73, 0xffff0000, v186
	v_lshlrev_b32_e32 v74, 16, v187
	v_and_b32_e32 v75, 0xffff0000, v187
	v_pk_add_f32 v[70:71], v[70:71], v[74:75]
	v_pk_add_f32 v[68:69], v[68:69], v[72:73]
	global_store_dwordx4 v[80:81], v[68:71], off offset:512
	s_nop 1
	v_lshlrev_b32_e32 v68, 16, v184
	v_and_b32_e32 v69, 0xffff0000, v184
	v_lshlrev_b32_e32 v70, 16, v185
	v_and_b32_e32 v71, 0xffff0000, v185
	v_pk_add_f32 v[66:67], v[66:67], v[70:71]
	v_pk_add_f32 v[64:65], v[64:65], v[68:69]
	global_store_dwordx4 v[80:81], v[64:67], off offset:576
	v_lshlrev_b32_e32 v68, 16, v183
	v_and_b32_e32 v69, 0xffff0000, v183
	v_lshlrev_b64 v[64:65], 12, v[168:169]
	v_lshlrev_b32_e32 v66, 16, v182
	v_and_b32_e32 v67, 0xffff0000, v182
	v_lshl_add_u64 v[64:65], s[78:79], 0, v[64:65]
	v_pk_add_f32 v[62:63], v[62:63], v[68:69]
	v_pk_add_f32 v[60:61], v[60:61], v[66:67]
	v_lshl_add_u64 v[64:65], v[64:65], 0, v[144:145]
	global_store_dwordx4 v[64:65], v[60:63], off
	s_nop 1
	v_lshlrev_b32_e32 v60, 16, v180
	v_and_b32_e32 v61, 0xffff0000, v180
	v_lshlrev_b32_e32 v62, 16, v181
	v_and_b32_e32 v63, 0xffff0000, v181
	v_pk_add_f32 v[58:59], v[58:59], v[62:63]
	v_pk_add_f32 v[56:57], v[56:57], v[60:61]
	global_store_dwordx4 v[64:65], v[56:59], off offset:64
	s_nop 1
	v_lshlrev_b32_e32 v56, 16, v176
	v_and_b32_e32 v57, 0xffff0000, v176
	v_lshlrev_b32_e32 v58, 16, v177
	v_and_b32_e32 v59, 0xffff0000, v177
	v_pk_add_f32 v[54:55], v[54:55], v[58:59]
	v_pk_add_f32 v[52:53], v[52:53], v[56:57]
	global_store_dwordx4 v[64:65], v[52:55], off offset:512
	s_nop 1
	v_lshlrev_b32_e32 v52, 16, v174
	v_and_b32_e32 v53, 0xffff0000, v174
	v_lshlrev_b32_e32 v54, 16, v175
	v_and_b32_e32 v55, 0xffff0000, v175
	v_pk_add_f32 v[46:47], v[46:47], v[54:55]
	v_pk_add_f32 v[44:45], v[44:45], v[52:53]
	global_store_dwordx4 v[64:65], v[44:47], off offset:576
	v_lshlrev_b64 v[52:53], 12, v[160:161]
	s_nop 0
	v_lshlrev_b32_e32 v44, 16, v172
	v_and_b32_e32 v45, 0xffff0000, v172
	v_lshlrev_b32_e32 v46, 16, v173
	v_and_b32_e32 v47, 0xffff0000, v173
	v_pk_add_f32 v[44:45], v[48:49], v[44:45]
	v_lshl_add_u64 v[48:49], s[78:79], 0, v[52:53]
	v_pk_add_f32 v[46:47], v[50:51], v[46:47]
	v_lshl_add_u64 v[48:49], v[48:49], 0, v[144:145]
	global_store_dwordx4 v[48:49], v[44:47], off
	s_nop 1
	v_lshlrev_b32_e32 v44, 16, v170
	v_and_b32_e32 v45, 0xffff0000, v170
	v_lshlrev_b32_e32 v46, 16, v171
	v_and_b32_e32 v47, 0xffff0000, v171
	v_pk_add_f32 v[42:43], v[42:43], v[46:47]
	v_pk_add_f32 v[40:41], v[40:41], v[44:45]
	global_store_dwordx4 v[48:49], v[40:43], off offset:64
	s_nop 1
	v_lshlrev_b32_e32 v40, 16, v166
	v_and_b32_e32 v41, 0xffff0000, v166
	v_lshlrev_b32_e32 v42, 16, v167
	v_and_b32_e32 v43, 0xffff0000, v167
	v_pk_add_f32 v[38:39], v[38:39], v[42:43]
	v_pk_add_f32 v[36:37], v[36:37], v[40:41]
	global_store_dwordx4 v[48:49], v[36:39], off offset:512
	s_nop 1
	v_lshlrev_b32_e32 v36, 16, v164
	v_and_b32_e32 v37, 0xffff0000, v164
	v_lshlrev_b32_e32 v38, 16, v165
	v_and_b32_e32 v39, 0xffff0000, v165
	v_pk_add_f32 v[30:31], v[30:31], v[38:39]
	v_pk_add_f32 v[28:29], v[28:29], v[36:37]
	global_store_dwordx4 v[48:49], v[28:31], off offset:576
	v_lshlrev_b64 v[36:37], 12, v[150:151]
	s_nop 0
	v_lshlrev_b32_e32 v28, 16, v162
	v_and_b32_e32 v29, 0xffff0000, v162
	v_lshlrev_b32_e32 v30, 16, v163
	v_and_b32_e32 v31, 0xffff0000, v163
	v_pk_add_f32 v[28:29], v[32:33], v[28:29]
	v_lshl_add_u64 v[32:33], s[78:79], 0, v[36:37]
	v_pk_add_f32 v[30:31], v[34:35], v[30:31]
	v_lshl_add_u64 v[32:33], v[32:33], 0, v[144:145]
	global_store_dwordx4 v[32:33], v[28:31], off
	s_nop 1
	v_lshlrev_b32_e32 v28, 16, v158
	v_and_b32_e32 v29, 0xffff0000, v158
	v_lshlrev_b32_e32 v30, 16, v159
	v_and_b32_e32 v31, 0xffff0000, v159
	v_pk_add_f32 v[26:27], v[26:27], v[30:31]
	v_pk_add_f32 v[24:25], v[24:25], v[28:29]
	global_store_dwordx4 v[32:33], v[24:27], off offset:64
	s_nop 1
	v_lshlrev_b32_e32 v24, 16, v156
	v_and_b32_e32 v25, 0xffff0000, v156
	v_lshlrev_b32_e32 v26, 16, v157
	v_and_b32_e32 v27, 0xffff0000, v157
	v_pk_add_f32 v[22:23], v[22:23], v[26:27]
	v_pk_add_f32 v[20:21], v[20:21], v[24:25]
	global_store_dwordx4 v[32:33], v[20:23], off offset:512
	s_nop 1
	v_lshlrev_b32_e32 v20, 16, v154
	v_and_b32_e32 v21, 0xffff0000, v154
	v_lshlrev_b32_e32 v22, 16, v155
	v_and_b32_e32 v23, 0xffff0000, v155
	v_pk_add_f32 v[14:15], v[14:15], v[22:23]
	v_pk_add_f32 v[12:13], v[12:13], v[20:21]
	global_store_dwordx4 v[32:33], v[12:15], off offset:576
	v_lshlrev_b64 v[20:21], 12, v[140:141]
	s_nop 0
	v_lshlrev_b32_e32 v12, 16, v152
	v_and_b32_e32 v13, 0xffff0000, v152
	v_lshlrev_b32_e32 v14, 16, v153
	v_and_b32_e32 v15, 0xffff0000, v153
	v_pk_add_f32 v[12:13], v[16:17], v[12:13]
	v_lshl_add_u64 v[16:17], s[78:79], 0, v[20:21]
	v_pk_add_f32 v[14:15], v[18:19], v[14:15]
	v_lshl_add_u64 v[16:17], v[16:17], 0, v[144:145]
	global_store_dwordx4 v[16:17], v[12:15], off
	s_nop 1
	v_lshlrev_b32_e32 v12, 16, v148
	v_and_b32_e32 v13, 0xffff0000, v148
	v_lshlrev_b32_e32 v14, 16, v149
	v_and_b32_e32 v15, 0xffff0000, v149
	v_pk_add_f32 v[10:11], v[10:11], v[14:15]
	v_pk_add_f32 v[8:9], v[8:9], v[12:13]
	global_store_dwordx4 v[16:17], v[8:11], off offset:64
	s_nop 1
	v_lshlrev_b32_e32 v8, 16, v146
	v_and_b32_e32 v9, 0xffff0000, v146
	v_lshlrev_b32_e32 v10, 16, v147
	v_and_b32_e32 v11, 0xffff0000, v147
	v_pk_add_f32 v[6:7], v[6:7], v[10:11]
	v_pk_add_f32 v[4:5], v[4:5], v[8:9]
	global_store_dwordx4 v[16:17], v[4:7], off offset:512
	s_nop 1
	v_lshlrev_b32_e32 v4, 16, v142
	v_and_b32_e32 v5, 0xffff0000, v142
	v_lshlrev_b32_e32 v6, 16, v143
	v_and_b32_e32 v7, 0xffff0000, v143
	v_pk_add_f32 v[2:3], v[2:3], v[6:7]
	v_pk_add_f32 v[0:1], v[0:1], v[4:5]
	global_store_dwordx4 v[16:17], v[0:3], off offset:576
	s_cbranch_vccz .LBB0_671
	s_waitcnt vmcnt(0)
	s_cmpk_gt_u32 s28, 0xff
	s_cbranch_scc1 .LBB0_682
	s_barrier
